# attention static priority given to waves 0-3 (older half) instead of waves 4-7, everything else as v34
# speedup vs baseline: 1.0017x; 1.0017x over previous
.LBB0_960:
	s_lshl_b32 s4, s44, 8
	s_ashr_i32 s5, s4, 31
	s_lshl_b64 s[4:5], s[4:5], 1
	s_waitcnt lgkmcnt(0)
	s_add_u32 s19, s10, s4
	s_addc_u32 s25, s11, s5
	v_readlane_b32 s11, v254, 36
	v_cvt_pk_bf16_f32 v44, v57, v49
	v_cvt_pk_bf16_f32 v45, v56, v48
	v_cvt_pk_bf16_f32 v46, v53, v51
	v_cvt_pk_bf16_f32 v47, v52, v50
	v_ashrrev_i32_e32 v48, 5, v62
	s_nop 0
	v_add_u32_e32 v51, s11, v64
	v_xor_b32_e32 v52, v51, v62
	v_lshlrev_b32_e32 v51, 13, v51
	v_lshlrev_b32_e32 v52, 4, v52
	s_movk_i32 s34, 0xf0
	v_readlane_b32 s10, v254, 12
	v_and_or_b32 v227, v52, s34, v51
	v_bfe_u32 v49, v62, 2, 2
	v_add_u32_e32 v51, s10, v48
	v_ashrrev_i32_e32 v52, 2, v51
	v_lshrrev_b32_e32 v50, 1, v62
	v_lshlrev_b32_e32 v53, 3, v52
	v_and_or_b32 v49, v50, 8, v49
	v_and_b32_e32 v53, 0x7fff0, v53
	v_and_b32_e32 v51, 4, v51
	v_and_b32_e32 v50, 3, v62
	v_or3_b32 v51, v53, v51, v49
	v_lshlrev_b32_e32 v53, 6, v48
	v_lshlrev_b32_e32 v52, 1, v52
	v_and_b32_e32 v53, 0xc0, v53
	v_bitop3_b32 v52, v52, v50, 2 bitop3:0x6c
	v_lshl_or_b32 v52, v52, 4, v53
	v_readlane_b32 s10, v254, 37
	v_lshl_or_b32 v228, v51, 13, v52
	s_add_u32 s6, s19, 0x38000000
	v_add_u32_e32 v51, s10, v64
	v_xor_b32_e32 v52, v51, v62
	v_readlane_b32 s10, v254, 38
	v_lshlrev_b32_e32 v51, 13, v51
	v_lshlrev_b32_e32 v52, 4, v52
	v_add_u32_e32 v48, s10, v48
	v_and_or_b32 v229, v52, s34, v51
	v_ashrrev_i32_e32 v51, 2, v48
	s_addc_u32 s7, s25, 0
	v_lshlrev_b32_e32 v52, 3, v51
	v_and_b32_e32 v53, 4, v48
	v_lshlrev_b32_e32 v48, 6, v48
	v_lshlrev_b32_e32 v51, 1, v51
	s_add_u32 s4, s8, s4
	v_and_b32_e32 v52, 0x7fff0, v52
	v_and_b32_e32 v48, 0xc0, v48
	v_bitop3_b32 v50, v51, v50, 2 bitop3:0x6c
	s_addc_u32 s5, s9, s5
	v_ashrrev_i32_e32 v96, 3, v62
	v_or3_b32 v49, v52, v53, v49
	v_lshl_or_b32 v48, v50, 4, v48
	s_add_u32 s28, s4, 0x38000100
	v_lshl_or_b32 v231, v49, 13, v48
	v_add_u32_e32 v48, s11, v96
	s_addc_u32 s29, s5, 0
	v_lshlrev_b32_e32 v49, 4, v62
	v_lshlrev_b32_e32 v50, 3, v48
	s_add_u32 s8, s30, 0x34000000
	v_xor_b32_e32 v49, v50, v49
	v_lshlrev_b32_e32 v48, 7, v48
	s_movk_i32 s10, 0x70
	s_mov_b32 m0, s18
	s_addc_u32 s9, s31, 0
	v_and_or_b32 v232, v49, s10, v48
	s_mov_b64 s[10:11], s[6:7]
	s_waitcnt vmcnt(0)
	s_cmpk_ge_u32 s97, 0x1000
	s_cbranch_scc1 .Lmy_prio_skip
	s_setprio 1
